# ph4 gates epilogue: n=1 column-half blocks interleaved with n=0 blocks so both 16B halves of each 32B sector are stored close in time; second-half params loaded up front; counted waits
# speedup vs baseline: 1.0110x; 1.0110x over previous
.LBB0_1002:
	v_mov_b32_e32 v66, v179
	s_and_b32 s2, s1, 1
	v_ashrrev_i32_e32 v67, 2, v66
	v_and_b32_e32 v67, 0xffffffc0, v67
	v_lshl_add_u32 v67, s0, 8, v67
	v_and_or_b32 v222, v66, 15, v67
	s_lshl_b32 s0, s1, 6
	v_lshrrev_b32_e32 v66, 1, v66
	s_and_b32 s0, s0, 0xffffff80
	v_and_b32_e32 v66, 0x78, v66
	v_or_b32_e32 v162, s0, v66
	s_mul_i32 s0, s2, 0x5000000
	v_ashrrev_i32_e32 v163, 31, v162
	s_add_u32 s0, s73, s0
	s_addc_u32 s1, s21, 0
	v_lshlrev_b64 v[170:171], 2, v[162:163]
	s_lshl_b32 s2, s2, 12
	v_lshl_add_u64 v[204:205], s[0:1], 0, v[170:171]
	s_add_u32 s0, s34, s2
	s_addc_u32 s1, s35, 0
	v_lshl_add_u64 v[206:207], s[0:1], 0, v[170:171]
	v_lshl_add_u64 v[66:67], v[162:163], 1, s[42:43]
	global_load_dwordx4 v[162:165], v[206:207], off
	s_add_u32 s0, s30, s2
	s_addc_u32 s1, s31, 0
	v_lshl_add_u64 v[208:209], s[0:1], 0, v[170:171]
	s_add_u32 s0, s16, s2
	v_ashrrev_i32_e32 v223, 31, v222
	s_addc_u32 s1, s17, 0
	v_lshlrev_b64 v[70:71], 11, v[222:223]
	v_lshl_add_u64 v[210:211], s[0:1], 0, v[170:171]
	v_lshl_add_u64 v[70:71], v[66:67], 0, v[70:71]
	global_load_dwordx4 v[170:173], v[210:211], off
	global_load_dwordx4 v[158:161], v[70:71], off
	global_load_dwordx4 v[166:169], v[208:209], off
	global_load_dwordx4 v[244:247], v[206:207], off offset:16
	global_load_dwordx4 v[248:251], v[208:209], off offset:16
	v_add_u32_e32 v214, 0x80, v222
	v_ashrrev_i32_e32 v215, 31, v214
	v_lshlrev_b64 v[68:69], 11, v[214:215]
	v_lshl_add_u64 v[68:69], v[66:67], 0, v[68:69]
	global_load_dwordx4 v[86:89], v[68:69], off
	v_or_b32_e32 v220, 16, v222
	v_add_u32_e32 v212, 0x90, v222
	v_ashrrev_i32_e32 v221, 31, v220
	v_ashrrev_i32_e32 v213, 31, v212
	v_lshlrev_b64 v[70:71], 11, v[220:221]
	v_or_b32_e32 v218, 32, v222
	v_lshlrev_b64 v[68:69], 11, v[212:213]
	v_lshl_add_u64 v[70:71], v[66:67], 0, v[70:71]
	v_ashrrev_i32_e32 v219, 31, v218
	v_lshl_add_u64 v[68:69], v[66:67], 0, v[68:69]
	global_load_dwordx4 v[122:125], v[70:71], off
	global_load_dwordx4 v[74:77], v[68:69], off
	v_lshlrev_b64 v[70:71], 11, v[218:219]
	v_or_b32_e32 v216, 48, v222
	v_add_u32_e32 v202, 0xa0, v222
	v_lshl_add_u64 v[70:71], v[66:67], 0, v[70:71]
	v_ashrrev_i32_e32 v217, 31, v216
	v_ashrrev_i32_e32 v203, 31, v202
	global_load_dwordx4 v[110:113], v[70:71], off
	v_lshlrev_b64 v[70:71], 11, v[216:217]
	v_lshlrev_b64 v[68:69], 11, v[202:203]
	v_add_u32_e32 v200, 0xb0, v222
	v_lshl_add_u64 v[70:71], v[66:67], 0, v[70:71]
	v_lshl_add_u64 v[68:69], v[66:67], 0, v[68:69]
	v_ashrrev_i32_e32 v201, 31, v200
	global_load_dwordx4 v[98:101], v[70:71], off
	s_waitcnt vmcnt(0)
	v_add_f32_e32 v154, v154, v162
	v_mul_f32_e32 v154, 0xbfb8aa3b, v154
	v_exp_f32_e32 v154, v154
	global_load_dwordx4 v[70:73], v[68:69], off
	v_lshlrev_b64 v[68:69], 11, v[200:201]
	v_lshl_add_u64 v[66:67], v[66:67], 0, v[68:69]
	v_add_f32_e32 v154, 1.0, v154
	v_rcp_f32_e64 v154, -v154
	global_load_dwordx4 v[66:69], v[66:67], off
	v_mul_f32_e32 v154, v170, v154
	v_lshlrev_b32_e32 v227, 16, v158
	v_and_b32_e32 v228, 0xffff0000, v158
	v_lshlrev_b32_e32 v226, 16, v159
	v_and_b32_e32 v158, 0xffff0000, v159
	v_add_f32_e32 v159, v154, v154
	v_mul_f32_e32 v159, 0x3fb8aa3b, v159
	v_add_f32_e32 v150, v150, v166
	v_exp_f32_e32 v159, v159
	v_mul_f32_e32 v150, 0xbfb8aa3b, v150
	v_exp_f32_e32 v150, v150
	v_add_f32_e32 v151, v151, v167
	v_sub_f32_e32 v159, 1.0, v159
	v_max_f32_e32 v159, 0x1e3ce508, v159
	v_add_f32_e32 v150, 1.0, v150
	v_mul_f32_e32 v229, v150, v159
	v_mul_f32_e32 v150, v150, v229
	v_rsq_f32_e32 v150, v150
	v_mul_f32_e32 v151, 0xbfb8aa3b, v151
	v_exp_f32_e32 v151, v151
	v_add_f32_e32 v152, v152, v168
	v_mul_f32_e32 v150, v159, v150
	v_mul_f32_e32 v150, v150, v227
	v_cvt_pk_bf16_f32 v150, v154, v150
	v_add_f32_e32 v154, v155, v163
	v_mul_f32_e32 v154, 0xbfb8aa3b, v154
	v_exp_f32_e32 v154, v154
	v_add_f32_e32 v151, 1.0, v151
	v_mul_f32_e32 v152, 0xbfb8aa3b, v152
	v_exp_f32_e32 v152, v152
	v_add_f32_e32 v154, 1.0, v154
	v_rcp_f32_e64 v154, -v154
	v_add_f32_e32 v153, v153, v169
	v_add_f32_e32 v152, 1.0, v152
	v_mul_f32_e32 v153, 0xbfb8aa3b, v153
	v_mul_f32_e32 v154, v171, v154
	v_add_f32_e32 v155, v154, v154
	v_mul_f32_e32 v155, 0x3fb8aa3b, v155
	v_exp_f32_e32 v155, v155
	v_exp_f32_e32 v153, v153
	v_sub_f32_e32 v155, 1.0, v155
	v_max_f32_e32 v155, 0x1e3ce508, v155
	v_mul_f32_e32 v159, v151, v155
	v_mul_f32_e32 v151, v151, v159
	v_rsq_f32_e32 v151, v151
	v_add_f32_e32 v153, 1.0, v153
	v_mul_f32_e32 v151, v155, v151
	v_mul_f32_e32 v151, v151, v228
	v_cvt_pk_bf16_f32 v151, v154, v151
	v_add_f32_e32 v154, v156, v164
	v_mul_f32_e32 v154, 0xbfb8aa3b, v154
	v_exp_f32_e32 v154, v154
	s_nop 0
	v_add_f32_e32 v154, 1.0, v154
	v_rcp_f32_e64 v154, -v154
	s_nop 0
	v_mul_f32_e32 v154, v172, v154
	v_add_f32_e32 v155, v154, v154
	v_mul_f32_e32 v155, 0x3fb8aa3b, v155
	v_exp_f32_e32 v155, v155
	s_nop 0
	v_sub_f32_e32 v155, 1.0, v155
	v_max_f32_e32 v155, 0x1e3ce508, v155
	v_mul_f32_e32 v156, v152, v155
	v_mul_f32_e32 v152, v152, v156
	v_rsq_f32_e32 v152, v152
	s_nop 0
	v_mul_f32_e32 v152, v155, v152
	v_mul_f32_e32 v152, v152, v226
	v_cvt_pk_bf16_f32 v152, v154, v152
	v_add_f32_e32 v154, v157, v165
	v_mul_f32_e32 v154, 0xbfb8aa3b, v154
	v_exp_f32_e32 v154, v154
	s_nop 0
	v_add_f32_e32 v154, 1.0, v154
	v_rcp_f32_e64 v154, -v154
	s_nop 0
	v_mul_f32_e32 v154, v173, v154
	v_add_f32_e32 v155, v154, v154
	v_mul_f32_e32 v155, 0x3fb8aa3b, v155
	v_exp_f32_e32 v155, v155
	s_nop 0
	v_sub_f32_e32 v155, 1.0, v155
	v_max_f32_e32 v155, 0x1e3ce508, v155
	v_mul_f32_e32 v156, v153, v155
	v_mul_f32_e32 v153, v153, v156
	v_rsq_f32_e32 v153, v153
	s_nop 0
	v_mul_f32_e32 v153, v155, v153
	v_mul_f32_e32 v153, v153, v158
	v_cvt_pk_bf16_f32 v153, v154, v153
	v_lshlrev_b64 v[154:155], 12, v[222:223]
	v_lshl_add_u64 v[154:155], v[204:205], 0, v[154:155]
	global_store_dwordx4 v[154:155], v[150:153], off
	global_load_dwordx4 v[226:229], v[210:211], off offset:16
	v_add_f32_e32 v146, v146, v162
	v_mul_f32_e32 v146, 0xbfb8aa3b, v146
	v_exp_f32_e32 v146, v146
	v_add_f32_e32 v142, v142, v166
	v_mul_f32_e32 v142, 0xbfb8aa3b, v142
	v_exp_f32_e32 v142, v142
	v_add_f32_e32 v146, 1.0, v146
	v_rcp_f32_e64 v146, -v146
	v_add_f32_e32 v147, v147, v163
	v_mul_f32_e32 v147, 0xbfb8aa3b, v147
	v_add_f32_e32 v142, 1.0, v142
	v_mul_f32_e32 v146, v170, v146
	v_add_f32_e32 v152, v146, v146
	v_mul_f32_e32 v152, 0x3fb8aa3b, v152
	v_exp_f32_e32 v152, v152
	v_exp_f32_e32 v147, v147
	v_lshlrev_b32_e32 v150, 16, v122
	v_add_f32_e32 v143, v143, v167
	v_sub_f32_e32 v152, 1.0, v152
	v_max_f32_e32 v152, 0x1e3ce508, v152
	v_mul_f32_e32 v153, v142, v152
	v_mul_f32_e32 v142, v142, v153
	v_rsq_f32_e32 v142, v142
	v_add_f32_e32 v147, 1.0, v147
	v_rcp_f32_e64 v147, -v147
	v_mul_f32_e32 v143, 0xbfb8aa3b, v143
	v_mul_f32_e32 v142, v152, v142
	v_mul_f32_e32 v142, v142, v150
	v_cvt_pk_bf16_f32 v142, v146, v142
	v_mul_f32_e32 v146, v171, v147
	v_add_f32_e32 v147, v146, v146
	v_mul_f32_e32 v147, 0x3fb8aa3b, v147
	v_exp_f32_e32 v147, v147
	v_exp_f32_e32 v143, v143
	v_add_f32_e32 v148, v148, v164
	v_mul_f32_e32 v148, 0xbfb8aa3b, v148
	v_sub_f32_e32 v147, 1.0, v147
	v_max_f32_e32 v147, 0x1e3ce508, v147
	v_add_f32_e32 v143, 1.0, v143
	v_exp_f32_e32 v148, v148
	v_mul_f32_e32 v150, v143, v147
	v_mul_f32_e32 v143, v143, v150
	v_rsq_f32_e32 v143, v143
	v_add_f32_e32 v148, 1.0, v148
	v_rcp_f32_e64 v148, -v148
	v_and_b32_e32 v122, 0xffff0000, v122
	v_mul_f32_e32 v143, v147, v143
	v_mul_f32_e32 v122, v143, v122
	v_cvt_pk_bf16_f32 v143, v146, v122
	v_add_f32_e32 v146, v149, v165
	v_mul_f32_e32 v146, 0xbfb8aa3b, v146
	v_mul_f32_e32 v148, v172, v148
	v_exp_f32_e32 v146, v146
	v_add_f32_e32 v150, v148, v148
	v_mul_f32_e32 v150, 0x3fb8aa3b, v150
	v_add_f32_e32 v144, v144, v168
	v_exp_f32_e32 v150, v150
	v_mul_f32_e32 v144, 0xbfb8aa3b, v144
	v_exp_f32_e32 v144, v144
	v_add_f32_e32 v146, 1.0, v146
	v_rcp_f32_e64 v146, -v146
	v_sub_f32_e32 v122, 1.0, v150
	v_max_f32_e32 v122, 0x1e3ce508, v122
	v_add_f32_e32 v144, 1.0, v144
	v_mul_f32_e32 v147, v144, v122
	v_mul_f32_e32 v146, v173, v146
	v_mul_f32_e32 v144, v144, v147
	v_add_f32_e32 v147, v146, v146
	v_mul_f32_e32 v147, 0x3fb8aa3b, v147
	v_add_f32_e32 v145, v145, v169
	v_exp_f32_e32 v147, v147
	v_mul_f32_e32 v145, 0xbfb8aa3b, v145
	v_exp_f32_e32 v145, v145
	v_rsq_f32_e32 v144, v144
	v_sub_f32_e32 v147, 1.0, v147
	v_max_f32_e32 v147, 0x1e3ce508, v147
	v_add_f32_e32 v145, 1.0, v145
	v_mul_f32_e32 v149, v145, v147
	v_mul_f32_e32 v145, v145, v149
	v_rsq_f32_e32 v145, v145
	v_lshlrev_b32_e32 v151, 16, v123
	v_mul_f32_e32 v122, v122, v144
	v_mul_f32_e32 v122, v122, v151
	v_and_b32_e32 v123, 0xffff0000, v123
	v_cvt_pk_bf16_f32 v144, v148, v122
	v_mul_f32_e32 v122, v147, v145
	v_mul_f32_e32 v122, v122, v123
	v_cvt_pk_bf16_f32 v145, v146, v122
	v_lshlrev_b64 v[122:123], 12, v[220:221]
	v_lshl_add_u64 v[122:123], v[204:205], 0, v[122:123]
	global_store_dwordx4 v[122:123], v[142:145], off
	v_lshlrev_b32_e32 v151, 16, v160
	v_and_b32_e32 v152, 0xffff0000, v160
	v_lshlrev_b32_e32 v153, 16, v161
	v_and_b32_e32 v150, 0xffff0000, v161
	s_waitcnt vmcnt(1)
	v_add_f32_e32 v62, v62, v244
	v_mul_f32_e32 v62, 0xbfb8aa3b, v62
	v_exp_f32_e32 v62, v62
	v_add_f32_e32 v58, v58, v248
	v_mul_f32_e32 v58, 0xbfb8aa3b, v58
	v_exp_f32_e32 v58, v58
	v_add_f32_e32 v62, 1.0, v62
	v_rcp_f32_e64 v62, -v62
	v_add_f32_e32 v59, v59, v249
	v_add_f32_e32 v58, 1.0, v58
	v_mul_f32_e32 v59, 0xbfb8aa3b, v59
	v_mul_f32_e32 v62, v226, v62
	v_add_f32_e32 v156, v62, v62
	v_mul_f32_e32 v156, 0x3fb8aa3b, v156
	v_exp_f32_e32 v156, v156
	v_exp_f32_e32 v59, v59
	v_add_f32_e32 v60, v60, v250
	v_mul_f32_e32 v60, 0xbfb8aa3b, v60
	v_sub_f32_e32 v156, 1.0, v156
	v_max_f32_e32 v156, 0x1e3ce508, v156
	v_mul_f32_e32 v157, v58, v156
	v_mul_f32_e32 v58, v58, v157
	v_rsq_f32_e32 v58, v58
	v_add_f32_e32 v59, 1.0, v59
	v_exp_f32_e32 v60, v60
	v_add_f32_e32 v61, v61, v251
	v_mul_f32_e32 v58, v156, v58
	v_mul_f32_e32 v58, v58, v151
	v_cvt_pk_bf16_f32 v58, v62, v58
	v_add_f32_e32 v62, v63, v245
	v_mul_f32_e32 v62, 0xbfb8aa3b, v62
	v_exp_f32_e32 v62, v62
	v_add_f32_e32 v60, 1.0, v60
	v_mul_f32_e32 v61, 0xbfb8aa3b, v61
	v_exp_f32_e32 v61, v61
	v_add_f32_e32 v62, 1.0, v62
	v_rcp_f32_e64 v62, -v62
	v_add_f32_e32 v61, 1.0, v61
	v_mul_f32_e32 v62, v227, v62
	v_add_f32_e32 v63, v62, v62
	v_mul_f32_e32 v63, 0x3fb8aa3b, v63
	v_exp_f32_e32 v63, v63
	s_nop 0
	v_sub_f32_e32 v63, 1.0, v63
	v_max_f32_e32 v63, 0x1e3ce508, v63
	v_mul_f32_e32 v151, v59, v63
	v_mul_f32_e32 v59, v59, v151
	v_rsq_f32_e32 v59, v59
	s_nop 0
	v_mul_f32_e32 v59, v63, v59
	v_mul_f32_e32 v59, v59, v152
	v_cvt_pk_bf16_f32 v59, v62, v59
	v_add_f32_e32 v62, v64, v246
	v_mul_f32_e32 v62, 0xbfb8aa3b, v62
	v_exp_f32_e32 v62, v62
	s_nop 0
	v_add_f32_e32 v62, 1.0, v62
	v_rcp_f32_e64 v62, -v62
	s_nop 0
	v_mul_f32_e32 v62, v228, v62
	v_add_f32_e32 v63, v62, v62
	v_mul_f32_e32 v63, 0x3fb8aa3b, v63
	v_exp_f32_e32 v63, v63
	s_nop 0
	v_sub_f32_e32 v63, 1.0, v63
	v_max_f32_e32 v63, 0x1e3ce508, v63
	v_mul_f32_e32 v64, v60, v63
	v_mul_f32_e32 v60, v60, v64
	v_rsq_f32_e32 v60, v60
	s_nop 0
	v_mul_f32_e32 v60, v63, v60
	v_mul_f32_e32 v60, v60, v153
	v_cvt_pk_bf16_f32 v60, v62, v60
	v_add_f32_e32 v62, v65, v247
	v_mul_f32_e32 v62, 0xbfb8aa3b, v62
	v_exp_f32_e32 v62, v62
	s_nop 0
	v_add_f32_e32 v62, 1.0, v62
	v_rcp_f32_e64 v62, -v62
	s_nop 0
	v_mul_f32_e32 v62, v229, v62
	v_add_f32_e32 v63, v62, v62
	v_mul_f32_e32 v63, 0x3fb8aa3b, v63
	v_exp_f32_e32 v63, v63
	s_nop 0
	v_sub_f32_e32 v63, 1.0, v63
	v_max_f32_e32 v63, 0x1e3ce508, v63
	v_mul_f32_e32 v64, v61, v63
	v_mul_f32_e32 v61, v61, v64
	v_rsq_f32_e32 v61, v61
	s_nop 0
	v_mul_f32_e32 v61, v63, v61
	v_mul_f32_e32 v61, v61, v150
	v_cvt_pk_bf16_f32 v61, v62, v61
	global_store_dwordx4 v[154:155], v[58:61], off offset:16
	v_add_f32_e32 v138, v138, v162
	v_mul_f32_e32 v138, 0xbfb8aa3b, v138
	v_exp_f32_e32 v138, v138
	v_add_f32_e32 v134, v134, v166
	v_mul_f32_e32 v134, 0xbfb8aa3b, v134
	v_exp_f32_e32 v134, v134
	v_add_f32_e32 v138, 1.0, v138
	v_rcp_f32_e64 v138, -v138
	v_add_f32_e32 v139, v139, v163
	v_mul_f32_e32 v139, 0xbfb8aa3b, v139
	v_add_f32_e32 v134, 1.0, v134
	v_mul_f32_e32 v138, v170, v138
	v_add_f32_e32 v144, v138, v138
	v_mul_f32_e32 v144, 0x3fb8aa3b, v144
	v_exp_f32_e32 v144, v144
	v_exp_f32_e32 v139, v139
	v_lshlrev_b32_e32 v142, 16, v110
	v_add_f32_e32 v135, v135, v167
	v_sub_f32_e32 v144, 1.0, v144
	v_max_f32_e32 v144, 0x1e3ce508, v144
	v_mul_f32_e32 v145, v134, v144
	v_mul_f32_e32 v134, v134, v145
	v_rsq_f32_e32 v134, v134
	v_add_f32_e32 v139, 1.0, v139
	v_rcp_f32_e64 v139, -v139
	v_mul_f32_e32 v135, 0xbfb8aa3b, v135
	v_mul_f32_e32 v134, v144, v134
	v_mul_f32_e32 v134, v134, v142
	v_cvt_pk_bf16_f32 v134, v138, v134
	v_mul_f32_e32 v138, v171, v139
	v_add_f32_e32 v139, v138, v138
	v_mul_f32_e32 v139, 0x3fb8aa3b, v139
	v_exp_f32_e32 v139, v139
	v_exp_f32_e32 v135, v135
	v_add_f32_e32 v140, v140, v164
	v_mul_f32_e32 v140, 0xbfb8aa3b, v140
	v_sub_f32_e32 v139, 1.0, v139
	v_max_f32_e32 v139, 0x1e3ce508, v139
	v_add_f32_e32 v135, 1.0, v135
	v_exp_f32_e32 v140, v140
	v_mul_f32_e32 v142, v135, v139
	v_mul_f32_e32 v135, v135, v142
	v_rsq_f32_e32 v135, v135
	v_add_f32_e32 v140, 1.0, v140
	v_rcp_f32_e64 v140, -v140
	v_and_b32_e32 v110, 0xffff0000, v110
	v_mul_f32_e32 v135, v139, v135
	v_mul_f32_e32 v110, v135, v110
	v_cvt_pk_bf16_f32 v135, v138, v110
	v_add_f32_e32 v138, v141, v165
	v_mul_f32_e32 v138, 0xbfb8aa3b, v138
	v_mul_f32_e32 v140, v172, v140
	v_exp_f32_e32 v138, v138
	v_add_f32_e32 v142, v140, v140
	v_mul_f32_e32 v142, 0x3fb8aa3b, v142
	v_add_f32_e32 v136, v136, v168
	v_exp_f32_e32 v142, v142
	v_mul_f32_e32 v136, 0xbfb8aa3b, v136
	v_exp_f32_e32 v136, v136
	v_add_f32_e32 v138, 1.0, v138
	v_rcp_f32_e64 v138, -v138
	v_sub_f32_e32 v110, 1.0, v142
	v_max_f32_e32 v110, 0x1e3ce508, v110
	v_add_f32_e32 v136, 1.0, v136
	v_mul_f32_e32 v139, v136, v110
	v_mul_f32_e32 v138, v173, v138
	v_mul_f32_e32 v136, v136, v139
	v_add_f32_e32 v139, v138, v138
	v_mul_f32_e32 v139, 0x3fb8aa3b, v139
	v_add_f32_e32 v137, v137, v169
	v_exp_f32_e32 v139, v139
	v_mul_f32_e32 v137, 0xbfb8aa3b, v137
	v_exp_f32_e32 v137, v137
	v_rsq_f32_e32 v136, v136
	v_sub_f32_e32 v139, 1.0, v139
	v_max_f32_e32 v139, 0x1e3ce508, v139
	v_add_f32_e32 v137, 1.0, v137
	v_mul_f32_e32 v141, v137, v139
	v_mul_f32_e32 v137, v137, v141
	v_rsq_f32_e32 v137, v137
	v_lshlrev_b32_e32 v143, 16, v111
	v_mul_f32_e32 v110, v110, v136
	v_mul_f32_e32 v110, v110, v143
	v_and_b32_e32 v111, 0xffff0000, v111
	v_cvt_pk_bf16_f32 v136, v140, v110
	v_mul_f32_e32 v110, v139, v137
	v_mul_f32_e32 v110, v110, v111
	v_cvt_pk_bf16_f32 v137, v138, v110
	v_lshlrev_b64 v[110:111], 12, v[218:219]
	v_lshl_add_u64 v[110:111], v[204:205], 0, v[110:111]
	global_store_dwordx4 v[110:111], v[134:137], off
	v_add_f32_e32 v54, v54, v244
	v_mul_f32_e32 v54, 0xbfb8aa3b, v54
	v_exp_f32_e32 v54, v54
	v_add_f32_e32 v50, v50, v248
	v_mul_f32_e32 v50, 0xbfb8aa3b, v50
	v_exp_f32_e32 v50, v50
	v_add_f32_e32 v54, 1.0, v54
	v_rcp_f32_e64 v54, -v54
	v_add_f32_e32 v55, v55, v245
	v_mul_f32_e32 v55, 0xbfb8aa3b, v55
	v_add_f32_e32 v50, 1.0, v50
	v_mul_f32_e32 v54, v226, v54
	v_add_f32_e32 v61, v54, v54
	v_mul_f32_e32 v61, 0x3fb8aa3b, v61
	v_exp_f32_e32 v61, v61
	v_exp_f32_e32 v55, v55
	v_lshlrev_b32_e32 v58, 16, v124
	v_add_f32_e32 v51, v51, v249
	v_sub_f32_e32 v61, 1.0, v61
	v_max_f32_e32 v61, 0x1e3ce508, v61
	v_mul_f32_e32 v62, v50, v61
	v_mul_f32_e32 v50, v50, v62
	v_rsq_f32_e32 v50, v50
	v_add_f32_e32 v55, 1.0, v55
	v_rcp_f32_e64 v55, -v55
	v_mul_f32_e32 v51, 0xbfb8aa3b, v51
	v_mul_f32_e32 v50, v61, v50
	v_mul_f32_e32 v50, v50, v58
	v_cvt_pk_bf16_f32 v50, v54, v50
	v_mul_f32_e32 v54, v227, v55
	v_add_f32_e32 v55, v54, v54
	v_mul_f32_e32 v55, 0x3fb8aa3b, v55
	v_exp_f32_e32 v55, v55
	v_exp_f32_e32 v51, v51
	v_add_f32_e32 v56, v56, v246
	v_mul_f32_e32 v56, 0xbfb8aa3b, v56
	v_sub_f32_e32 v55, 1.0, v55
	v_exp_f32_e32 v56, v56
	v_max_f32_e32 v55, 0x1e3ce508, v55
	v_add_f32_e32 v51, 1.0, v51
	v_mul_f32_e32 v58, v51, v55
	v_mul_f32_e32 v51, v51, v58
	v_rsq_f32_e32 v51, v51
	v_add_f32_e32 v56, 1.0, v56
	v_rcp_f32_e64 v56, -v56
	v_add_f32_e32 v52, v52, v250
	v_mul_f32_e32 v51, v55, v51
	v_add_f32_e32 v55, v57, v247
	v_mul_f32_e32 v55, 0xbfb8aa3b, v55
	v_mul_f32_e32 v56, v228, v56
	v_exp_f32_e32 v55, v55
	v_add_f32_e32 v58, v56, v56
	v_mul_f32_e32 v58, 0x3fb8aa3b, v58
	v_exp_f32_e32 v58, v58
	v_mul_f32_e32 v52, 0xbfb8aa3b, v52
	v_exp_f32_e32 v52, v52
	v_add_f32_e32 v55, 1.0, v55
	v_and_b32_e32 v59, 0xffff0000, v124
	v_rcp_f32_e64 v55, -v55
	v_mul_f32_e32 v51, v51, v59
	v_cvt_pk_bf16_f32 v51, v54, v51
	v_sub_f32_e32 v54, 1.0, v58
	v_max_f32_e32 v54, 0x1e3ce508, v54
	v_add_f32_e32 v52, 1.0, v52
	v_mul_f32_e32 v57, v52, v54
	v_mul_f32_e32 v55, v229, v55
	v_mul_f32_e32 v52, v52, v57
	v_add_f32_e32 v57, v55, v55
	v_mul_f32_e32 v57, 0x3fb8aa3b, v57
	v_add_f32_e32 v53, v53, v251
	v_exp_f32_e32 v57, v57
	v_mul_f32_e32 v53, 0xbfb8aa3b, v53
	v_exp_f32_e32 v53, v53
	v_rsq_f32_e32 v52, v52
	v_sub_f32_e32 v57, 1.0, v57
	v_max_f32_e32 v57, 0x1e3ce508, v57
	v_add_f32_e32 v53, 1.0, v53
	v_mul_f32_e32 v58, v53, v57
	v_mul_f32_e32 v53, v53, v58
	v_rsq_f32_e32 v53, v53
	v_lshlrev_b32_e32 v60, 16, v125
	v_and_b32_e32 v62, 0xffff0000, v125
	v_mul_f32_e32 v52, v54, v52
	v_mul_f32_e32 v53, v57, v53
	v_mul_f32_e32 v52, v52, v60
	v_mul_f32_e32 v53, v53, v62
	v_cvt_pk_bf16_f32 v52, v56, v52
	v_cvt_pk_bf16_f32 v53, v55, v53
	global_store_dwordx4 v[122:123], v[50:53], off offset:16
	v_add_f32_e32 v130, v130, v162
	v_mul_f32_e32 v130, 0xbfb8aa3b, v130
	v_exp_f32_e32 v130, v130
	v_add_f32_e32 v126, v126, v166
	v_mul_f32_e32 v126, 0xbfb8aa3b, v126
	v_exp_f32_e32 v126, v126
	v_add_f32_e32 v130, 1.0, v130
	v_rcp_f32_e64 v130, -v130
	v_add_f32_e32 v131, v131, v163
	v_mul_f32_e32 v131, 0xbfb8aa3b, v131
	v_add_f32_e32 v126, 1.0, v126
	v_mul_f32_e32 v130, v170, v130
	v_add_f32_e32 v136, v130, v130
	v_mul_f32_e32 v136, 0x3fb8aa3b, v136
	v_exp_f32_e32 v136, v136
	v_exp_f32_e32 v131, v131
	v_lshlrev_b32_e32 v134, 16, v98
	v_add_f32_e32 v127, v127, v167
	v_sub_f32_e32 v136, 1.0, v136
	v_max_f32_e32 v136, 0x1e3ce508, v136
	v_mul_f32_e32 v137, v126, v136
	v_mul_f32_e32 v126, v126, v137
	v_rsq_f32_e32 v126, v126
	v_add_f32_e32 v131, 1.0, v131
	v_rcp_f32_e64 v131, -v131
	v_mul_f32_e32 v127, 0xbfb8aa3b, v127
	v_mul_f32_e32 v126, v136, v126
	v_mul_f32_e32 v126, v126, v134
	v_cvt_pk_bf16_f32 v126, v130, v126
	v_mul_f32_e32 v130, v171, v131
	v_add_f32_e32 v131, v130, v130
	v_mul_f32_e32 v131, 0x3fb8aa3b, v131
	v_exp_f32_e32 v131, v131
	v_exp_f32_e32 v127, v127
	v_add_f32_e32 v132, v132, v164
	v_mul_f32_e32 v132, 0xbfb8aa3b, v132
	v_sub_f32_e32 v131, 1.0, v131
	v_max_f32_e32 v131, 0x1e3ce508, v131
	v_add_f32_e32 v127, 1.0, v127
	v_exp_f32_e32 v132, v132
	v_mul_f32_e32 v134, v127, v131
	v_mul_f32_e32 v127, v127, v134
	v_rsq_f32_e32 v127, v127
	v_add_f32_e32 v132, 1.0, v132
	v_rcp_f32_e64 v132, -v132
	v_and_b32_e32 v98, 0xffff0000, v98
	v_mul_f32_e32 v127, v131, v127
	v_mul_f32_e32 v98, v127, v98
	v_cvt_pk_bf16_f32 v127, v130, v98
	v_add_f32_e32 v130, v133, v165
	v_mul_f32_e32 v130, 0xbfb8aa3b, v130
	v_mul_f32_e32 v132, v172, v132
	v_exp_f32_e32 v130, v130
	v_add_f32_e32 v134, v132, v132
	v_mul_f32_e32 v134, 0x3fb8aa3b, v134
	v_add_f32_e32 v128, v128, v168
	v_exp_f32_e32 v134, v134
	v_mul_f32_e32 v128, 0xbfb8aa3b, v128
	v_exp_f32_e32 v128, v128
	v_add_f32_e32 v130, 1.0, v130
	v_rcp_f32_e64 v130, -v130
	v_sub_f32_e32 v98, 1.0, v134
	v_max_f32_e32 v98, 0x1e3ce508, v98
	v_add_f32_e32 v128, 1.0, v128
	v_mul_f32_e32 v131, v128, v98
	v_mul_f32_e32 v130, v173, v130
	v_mul_f32_e32 v128, v128, v131
	v_add_f32_e32 v131, v130, v130
	v_mul_f32_e32 v131, 0x3fb8aa3b, v131
	v_add_f32_e32 v129, v129, v169
	v_exp_f32_e32 v131, v131
	v_mul_f32_e32 v129, 0xbfb8aa3b, v129
	v_exp_f32_e32 v129, v129
	v_rsq_f32_e32 v128, v128
	v_sub_f32_e32 v131, 1.0, v131
	v_max_f32_e32 v131, 0x1e3ce508, v131
	v_add_f32_e32 v129, 1.0, v129
	v_mul_f32_e32 v133, v129, v131
	v_mul_f32_e32 v129, v129, v133
	v_rsq_f32_e32 v129, v129
	v_lshlrev_b32_e32 v135, 16, v99
	v_mul_f32_e32 v98, v98, v128
	v_mul_f32_e32 v98, v98, v135
	v_and_b32_e32 v99, 0xffff0000, v99
	v_cvt_pk_bf16_f32 v128, v132, v98
	v_mul_f32_e32 v98, v131, v129
	v_mul_f32_e32 v98, v98, v99
	v_cvt_pk_bf16_f32 v129, v130, v98
	v_lshlrev_b64 v[98:99], 12, v[216:217]
	v_lshl_add_u64 v[98:99], v[204:205], 0, v[98:99]
	global_store_dwordx4 v[98:99], v[126:129], off
	v_add_f32_e32 v46, v46, v244
	v_mul_f32_e32 v46, 0xbfb8aa3b, v46
	v_exp_f32_e32 v46, v46
	v_add_f32_e32 v42, v42, v248
	v_mul_f32_e32 v42, 0xbfb8aa3b, v42
	v_exp_f32_e32 v42, v42
	v_add_f32_e32 v46, 1.0, v46
	v_rcp_f32_e64 v46, -v46
	v_add_f32_e32 v47, v47, v245
	v_mul_f32_e32 v47, 0xbfb8aa3b, v47
	v_add_f32_e32 v42, 1.0, v42
	v_mul_f32_e32 v46, v226, v46
	v_add_f32_e32 v53, v46, v46
	v_mul_f32_e32 v53, 0x3fb8aa3b, v53
	v_exp_f32_e32 v53, v53
	v_exp_f32_e32 v47, v47
	v_lshlrev_b32_e32 v50, 16, v112
	v_add_f32_e32 v43, v43, v249
	v_sub_f32_e32 v53, 1.0, v53
	v_max_f32_e32 v53, 0x1e3ce508, v53
	v_mul_f32_e32 v54, v42, v53
	v_mul_f32_e32 v42, v42, v54
	v_rsq_f32_e32 v42, v42
	v_add_f32_e32 v47, 1.0, v47
	v_rcp_f32_e64 v47, -v47
	v_mul_f32_e32 v43, 0xbfb8aa3b, v43
	v_mul_f32_e32 v42, v53, v42
	v_mul_f32_e32 v42, v42, v50
	v_cvt_pk_bf16_f32 v42, v46, v42
	v_mul_f32_e32 v46, v227, v47
	v_add_f32_e32 v47, v46, v46
	v_mul_f32_e32 v47, 0x3fb8aa3b, v47
	v_exp_f32_e32 v47, v47
	v_exp_f32_e32 v43, v43
	v_add_f32_e32 v48, v48, v246
	v_mul_f32_e32 v48, 0xbfb8aa3b, v48
	v_sub_f32_e32 v47, 1.0, v47
	v_exp_f32_e32 v48, v48
	v_max_f32_e32 v47, 0x1e3ce508, v47
	v_add_f32_e32 v43, 1.0, v43
	v_mul_f32_e32 v50, v43, v47
	v_mul_f32_e32 v43, v43, v50
	v_rsq_f32_e32 v43, v43
	v_add_f32_e32 v48, 1.0, v48
	v_rcp_f32_e64 v48, -v48
	v_add_f32_e32 v44, v44, v250
	v_mul_f32_e32 v43, v47, v43
	v_add_f32_e32 v47, v49, v247
	v_mul_f32_e32 v47, 0xbfb8aa3b, v47
	v_mul_f32_e32 v48, v228, v48
	v_exp_f32_e32 v47, v47
	v_add_f32_e32 v50, v48, v48
	v_mul_f32_e32 v50, 0x3fb8aa3b, v50
	v_exp_f32_e32 v50, v50
	v_mul_f32_e32 v44, 0xbfb8aa3b, v44
	v_exp_f32_e32 v44, v44
	v_add_f32_e32 v47, 1.0, v47
	v_and_b32_e32 v51, 0xffff0000, v112
	v_rcp_f32_e64 v47, -v47
	v_mul_f32_e32 v43, v43, v51
	v_cvt_pk_bf16_f32 v43, v46, v43
	v_sub_f32_e32 v46, 1.0, v50
	v_max_f32_e32 v46, 0x1e3ce508, v46
	v_add_f32_e32 v44, 1.0, v44
	v_mul_f32_e32 v49, v44, v46
	v_mul_f32_e32 v47, v229, v47
	v_mul_f32_e32 v44, v44, v49
	v_add_f32_e32 v49, v47, v47
	v_mul_f32_e32 v49, 0x3fb8aa3b, v49
	v_add_f32_e32 v45, v45, v251
	v_exp_f32_e32 v49, v49
	v_mul_f32_e32 v45, 0xbfb8aa3b, v45
	v_exp_f32_e32 v45, v45
	v_rsq_f32_e32 v44, v44
	v_sub_f32_e32 v49, 1.0, v49
	v_max_f32_e32 v49, 0x1e3ce508, v49
	v_add_f32_e32 v45, 1.0, v45
	v_mul_f32_e32 v50, v45, v49
	v_mul_f32_e32 v45, v45, v50
	v_rsq_f32_e32 v45, v45
	v_lshlrev_b32_e32 v52, 16, v113
	v_and_b32_e32 v54, 0xffff0000, v113
	v_mul_f32_e32 v44, v46, v44
	v_mul_f32_e32 v45, v49, v45
	v_mul_f32_e32 v44, v44, v52
	v_mul_f32_e32 v45, v45, v54
	v_cvt_pk_bf16_f32 v44, v48, v44
	v_cvt_pk_bf16_f32 v45, v47, v45
	global_store_dwordx4 v[110:111], v[42:45], off offset:16
	v_add_f32_e32 v118, v118, v162
	v_mul_f32_e32 v118, 0xbfb8aa3b, v118
	v_exp_f32_e32 v118, v118
	v_add_f32_e32 v114, v114, v166
	v_mul_f32_e32 v114, 0xbfb8aa3b, v114
	v_exp_f32_e32 v114, v114
	v_add_f32_e32 v118, 1.0, v118
	v_rcp_f32_e64 v118, -v118
	v_add_f32_e32 v119, v119, v163
	v_mul_f32_e32 v119, 0xbfb8aa3b, v119
	v_add_f32_e32 v114, 1.0, v114
	v_mul_f32_e32 v118, v170, v118
	v_add_f32_e32 v128, v118, v118
	v_mul_f32_e32 v128, 0x3fb8aa3b, v128
	v_exp_f32_e32 v128, v128
	v_exp_f32_e32 v119, v119
	v_lshlrev_b32_e32 v126, 16, v86
	v_add_f32_e32 v115, v115, v167
	v_sub_f32_e32 v128, 1.0, v128
	v_max_f32_e32 v128, 0x1e3ce508, v128
	v_mul_f32_e32 v129, v114, v128
	v_mul_f32_e32 v114, v114, v129
	v_rsq_f32_e32 v114, v114
	v_add_f32_e32 v119, 1.0, v119
	v_rcp_f32_e64 v119, -v119
	v_mul_f32_e32 v115, 0xbfb8aa3b, v115
	v_mul_f32_e32 v114, v128, v114
	v_mul_f32_e32 v114, v114, v126
	v_cvt_pk_bf16_f32 v114, v118, v114
	v_mul_f32_e32 v118, v171, v119
	v_add_f32_e32 v119, v118, v118
	v_mul_f32_e32 v119, 0x3fb8aa3b, v119
	v_exp_f32_e32 v119, v119
	v_exp_f32_e32 v115, v115
	v_add_f32_e32 v120, v120, v164
	v_mul_f32_e32 v120, 0xbfb8aa3b, v120
	v_sub_f32_e32 v119, 1.0, v119
	v_max_f32_e32 v119, 0x1e3ce508, v119
	v_add_f32_e32 v115, 1.0, v115
	v_exp_f32_e32 v120, v120
	v_mul_f32_e32 v126, v115, v119
	v_mul_f32_e32 v115, v115, v126
	v_rsq_f32_e32 v115, v115
	v_add_f32_e32 v120, 1.0, v120
	v_rcp_f32_e64 v120, -v120
	v_and_b32_e32 v86, 0xffff0000, v86
	v_mul_f32_e32 v115, v119, v115
	v_mul_f32_e32 v86, v115, v86
	v_cvt_pk_bf16_f32 v115, v118, v86
	v_add_f32_e32 v118, v121, v165
	v_mul_f32_e32 v118, 0xbfb8aa3b, v118
	v_mul_f32_e32 v120, v172, v120
	v_exp_f32_e32 v118, v118
	v_add_f32_e32 v126, v120, v120
	v_mul_f32_e32 v126, 0x3fb8aa3b, v126
	v_add_f32_e32 v116, v116, v168
	v_exp_f32_e32 v126, v126
	v_mul_f32_e32 v116, 0xbfb8aa3b, v116
	v_exp_f32_e32 v116, v116
	v_add_f32_e32 v118, 1.0, v118
	v_rcp_f32_e64 v118, -v118
	v_sub_f32_e32 v86, 1.0, v126
	v_max_f32_e32 v86, 0x1e3ce508, v86
	v_add_f32_e32 v116, 1.0, v116
	v_mul_f32_e32 v119, v116, v86
	v_mul_f32_e32 v118, v173, v118
	v_mul_f32_e32 v116, v116, v119
	v_add_f32_e32 v119, v118, v118
	v_mul_f32_e32 v119, 0x3fb8aa3b, v119
	v_add_f32_e32 v117, v117, v169
	v_exp_f32_e32 v119, v119
	v_mul_f32_e32 v117, 0xbfb8aa3b, v117
	v_exp_f32_e32 v117, v117
	v_rsq_f32_e32 v116, v116
	v_sub_f32_e32 v119, 1.0, v119
	v_max_f32_e32 v119, 0x1e3ce508, v119
	v_add_f32_e32 v117, 1.0, v117
	v_mul_f32_e32 v121, v117, v119
	v_mul_f32_e32 v117, v117, v121
	v_rsq_f32_e32 v117, v117
	v_lshlrev_b32_e32 v127, 16, v87
	v_mul_f32_e32 v86, v86, v116
	v_mul_f32_e32 v86, v86, v127
	v_and_b32_e32 v87, 0xffff0000, v87
	v_cvt_pk_bf16_f32 v116, v120, v86
	v_mul_f32_e32 v86, v119, v117
	v_mul_f32_e32 v86, v86, v87
	v_cvt_pk_bf16_f32 v117, v118, v86
	v_lshlrev_b64 v[86:87], 12, v[214:215]
	v_lshl_add_u64 v[86:87], v[204:205], 0, v[86:87]
	global_store_dwordx4 v[86:87], v[114:117], off
	v_add_f32_e32 v38, v38, v244
	v_mul_f32_e32 v38, 0xbfb8aa3b, v38
	v_exp_f32_e32 v38, v38
	v_add_f32_e32 v34, v34, v248
	v_mul_f32_e32 v34, 0xbfb8aa3b, v34
	v_exp_f32_e32 v34, v34
	v_add_f32_e32 v38, 1.0, v38
	v_rcp_f32_e64 v38, -v38
	v_add_f32_e32 v39, v39, v245
	v_mul_f32_e32 v39, 0xbfb8aa3b, v39
	v_add_f32_e32 v34, 1.0, v34
	v_mul_f32_e32 v38, v226, v38
	v_add_f32_e32 v45, v38, v38
	v_mul_f32_e32 v45, 0x3fb8aa3b, v45
	v_exp_f32_e32 v45, v45
	v_exp_f32_e32 v39, v39
	v_lshlrev_b32_e32 v42, 16, v100
	v_add_f32_e32 v35, v35, v249
	v_sub_f32_e32 v45, 1.0, v45
	v_max_f32_e32 v45, 0x1e3ce508, v45
	v_mul_f32_e32 v46, v34, v45
	v_mul_f32_e32 v34, v34, v46
	v_rsq_f32_e32 v34, v34
	v_add_f32_e32 v39, 1.0, v39
	v_rcp_f32_e64 v39, -v39
	v_mul_f32_e32 v35, 0xbfb8aa3b, v35
	v_mul_f32_e32 v34, v45, v34
	v_mul_f32_e32 v34, v34, v42
	v_cvt_pk_bf16_f32 v34, v38, v34
	v_mul_f32_e32 v38, v227, v39
	v_add_f32_e32 v39, v38, v38
	v_mul_f32_e32 v39, 0x3fb8aa3b, v39
	v_exp_f32_e32 v39, v39
	v_exp_f32_e32 v35, v35
	v_add_f32_e32 v40, v40, v246
	v_mul_f32_e32 v40, 0xbfb8aa3b, v40
	v_sub_f32_e32 v39, 1.0, v39
	v_exp_f32_e32 v40, v40
	v_max_f32_e32 v39, 0x1e3ce508, v39
	v_add_f32_e32 v35, 1.0, v35
	v_mul_f32_e32 v42, v35, v39
	v_mul_f32_e32 v35, v35, v42
	v_rsq_f32_e32 v35, v35
	v_add_f32_e32 v40, 1.0, v40
	v_rcp_f32_e64 v40, -v40
	v_add_f32_e32 v36, v36, v250
	v_mul_f32_e32 v35, v39, v35
	v_add_f32_e32 v39, v41, v247
	v_mul_f32_e32 v39, 0xbfb8aa3b, v39
	v_mul_f32_e32 v40, v228, v40
	v_exp_f32_e32 v39, v39
	v_add_f32_e32 v42, v40, v40
	v_mul_f32_e32 v42, 0x3fb8aa3b, v42
	v_exp_f32_e32 v42, v42
	v_mul_f32_e32 v36, 0xbfb8aa3b, v36
	v_exp_f32_e32 v36, v36
	v_add_f32_e32 v39, 1.0, v39
	v_and_b32_e32 v43, 0xffff0000, v100
	v_rcp_f32_e64 v39, -v39
	v_mul_f32_e32 v35, v35, v43
	v_cvt_pk_bf16_f32 v35, v38, v35
	v_sub_f32_e32 v38, 1.0, v42
	v_max_f32_e32 v38, 0x1e3ce508, v38
	v_add_f32_e32 v36, 1.0, v36
	v_mul_f32_e32 v41, v36, v38
	v_mul_f32_e32 v39, v229, v39
	v_mul_f32_e32 v36, v36, v41
	v_add_f32_e32 v41, v39, v39
	v_mul_f32_e32 v41, 0x3fb8aa3b, v41
	v_add_f32_e32 v37, v37, v251
	v_exp_f32_e32 v41, v41
	v_mul_f32_e32 v37, 0xbfb8aa3b, v37
	v_exp_f32_e32 v37, v37
	v_rsq_f32_e32 v36, v36
	v_sub_f32_e32 v41, 1.0, v41
	v_max_f32_e32 v41, 0x1e3ce508, v41
	v_add_f32_e32 v37, 1.0, v37
	v_mul_f32_e32 v42, v37, v41
	v_mul_f32_e32 v37, v37, v42
	v_rsq_f32_e32 v37, v37
	v_lshlrev_b32_e32 v44, 16, v101
	v_and_b32_e32 v46, 0xffff0000, v101
	v_mul_f32_e32 v36, v38, v36
	v_mul_f32_e32 v37, v41, v37
	v_mul_f32_e32 v36, v36, v44
	v_mul_f32_e32 v37, v37, v46
	v_cvt_pk_bf16_f32 v36, v40, v36
	v_cvt_pk_bf16_f32 v37, v39, v37
	global_store_dwordx4 v[98:99], v[34:37], off offset:16
	v_add_f32_e32 v106, v106, v162
	v_mul_f32_e32 v106, 0xbfb8aa3b, v106
	v_exp_f32_e32 v106, v106
	v_add_f32_e32 v102, v102, v166
	v_mul_f32_e32 v102, 0xbfb8aa3b, v102
	v_exp_f32_e32 v102, v102
	v_add_f32_e32 v106, 1.0, v106
	v_rcp_f32_e64 v106, -v106
	v_add_f32_e32 v107, v107, v163
	v_mul_f32_e32 v107, 0xbfb8aa3b, v107
	v_add_f32_e32 v102, 1.0, v102
	v_mul_f32_e32 v106, v170, v106
	v_add_f32_e32 v116, v106, v106
	v_mul_f32_e32 v116, 0x3fb8aa3b, v116
	v_exp_f32_e32 v116, v116
	v_exp_f32_e32 v107, v107
	v_lshlrev_b32_e32 v114, 16, v74
	v_add_f32_e32 v103, v103, v167
	v_sub_f32_e32 v116, 1.0, v116
	v_max_f32_e32 v116, 0x1e3ce508, v116
	v_mul_f32_e32 v117, v102, v116
	v_mul_f32_e32 v102, v102, v117
	v_rsq_f32_e32 v102, v102
	v_add_f32_e32 v107, 1.0, v107
	v_rcp_f32_e64 v107, -v107
	v_mul_f32_e32 v103, 0xbfb8aa3b, v103
	v_mul_f32_e32 v102, v116, v102
	v_mul_f32_e32 v102, v102, v114
	v_cvt_pk_bf16_f32 v102, v106, v102
	v_mul_f32_e32 v106, v171, v107
	v_add_f32_e32 v107, v106, v106
	v_mul_f32_e32 v107, 0x3fb8aa3b, v107
	v_exp_f32_e32 v107, v107
	v_exp_f32_e32 v103, v103
	v_add_f32_e32 v108, v108, v164
	v_mul_f32_e32 v108, 0xbfb8aa3b, v108
	v_sub_f32_e32 v107, 1.0, v107
	v_max_f32_e32 v107, 0x1e3ce508, v107
	v_add_f32_e32 v103, 1.0, v103
	v_exp_f32_e32 v108, v108
	v_mul_f32_e32 v114, v103, v107
	v_mul_f32_e32 v103, v103, v114
	v_rsq_f32_e32 v103, v103
	v_add_f32_e32 v108, 1.0, v108
	v_rcp_f32_e64 v108, -v108
	v_and_b32_e32 v74, 0xffff0000, v74
	v_mul_f32_e32 v103, v107, v103
	v_mul_f32_e32 v74, v103, v74
	v_cvt_pk_bf16_f32 v103, v106, v74
	v_add_f32_e32 v106, v109, v165
	v_mul_f32_e32 v106, 0xbfb8aa3b, v106
	v_mul_f32_e32 v108, v172, v108
	v_exp_f32_e32 v106, v106
	v_add_f32_e32 v114, v108, v108
	v_mul_f32_e32 v114, 0x3fb8aa3b, v114
	v_add_f32_e32 v104, v104, v168
	v_exp_f32_e32 v114, v114
	v_mul_f32_e32 v104, 0xbfb8aa3b, v104
	v_exp_f32_e32 v104, v104
	v_add_f32_e32 v106, 1.0, v106
	v_rcp_f32_e64 v106, -v106
	v_sub_f32_e32 v74, 1.0, v114
	v_max_f32_e32 v74, 0x1e3ce508, v74
	v_add_f32_e32 v104, 1.0, v104
	v_mul_f32_e32 v107, v104, v74
	v_mul_f32_e32 v106, v173, v106
	v_mul_f32_e32 v104, v104, v107
	v_add_f32_e32 v107, v106, v106
	v_mul_f32_e32 v107, 0x3fb8aa3b, v107
	v_add_f32_e32 v105, v105, v169
	v_exp_f32_e32 v107, v107
	v_mul_f32_e32 v105, 0xbfb8aa3b, v105
	v_exp_f32_e32 v105, v105
	v_rsq_f32_e32 v104, v104
	v_sub_f32_e32 v107, 1.0, v107
	v_max_f32_e32 v107, 0x1e3ce508, v107
	v_add_f32_e32 v105, 1.0, v105
	v_mul_f32_e32 v109, v105, v107
	v_mul_f32_e32 v105, v105, v109
	v_rsq_f32_e32 v105, v105
	v_lshlrev_b32_e32 v115, 16, v75
	v_mul_f32_e32 v74, v74, v104
	v_mul_f32_e32 v74, v74, v115
	v_and_b32_e32 v75, 0xffff0000, v75
	v_cvt_pk_bf16_f32 v104, v108, v74
	v_mul_f32_e32 v74, v107, v105
	v_mul_f32_e32 v74, v74, v75
	v_cvt_pk_bf16_f32 v105, v106, v74
	v_lshlrev_b64 v[74:75], 12, v[212:213]
	v_lshl_add_u64 v[74:75], v[204:205], 0, v[74:75]
	global_store_dwordx4 v[74:75], v[102:105], off
	v_add_f32_e32 v30, v30, v244
	v_mul_f32_e32 v30, 0xbfb8aa3b, v30
	v_exp_f32_e32 v30, v30
	v_add_f32_e32 v26, v26, v248
	v_mul_f32_e32 v26, 0xbfb8aa3b, v26
	v_exp_f32_e32 v26, v26
	v_add_f32_e32 v30, 1.0, v30
	v_rcp_f32_e64 v30, -v30
	v_add_f32_e32 v31, v31, v245
	v_mul_f32_e32 v31, 0xbfb8aa3b, v31
	v_add_f32_e32 v26, 1.0, v26
	v_mul_f32_e32 v30, v226, v30
	v_add_f32_e32 v37, v30, v30
	v_mul_f32_e32 v37, 0x3fb8aa3b, v37
	v_exp_f32_e32 v37, v37
	v_exp_f32_e32 v31, v31
	v_lshlrev_b32_e32 v34, 16, v88
	v_add_f32_e32 v27, v27, v249
	v_sub_f32_e32 v37, 1.0, v37
	v_max_f32_e32 v37, 0x1e3ce508, v37
	v_mul_f32_e32 v38, v26, v37
	v_mul_f32_e32 v26, v26, v38
	v_rsq_f32_e32 v26, v26
	v_add_f32_e32 v31, 1.0, v31
	v_rcp_f32_e64 v31, -v31
	v_mul_f32_e32 v27, 0xbfb8aa3b, v27
	v_mul_f32_e32 v26, v37, v26
	v_mul_f32_e32 v26, v26, v34
	v_cvt_pk_bf16_f32 v26, v30, v26
	v_mul_f32_e32 v30, v227, v31
	v_add_f32_e32 v31, v30, v30
	v_mul_f32_e32 v31, 0x3fb8aa3b, v31
	v_exp_f32_e32 v31, v31
	v_exp_f32_e32 v27, v27
	v_add_f32_e32 v32, v32, v246
	v_mul_f32_e32 v32, 0xbfb8aa3b, v32
	v_sub_f32_e32 v31, 1.0, v31
	v_exp_f32_e32 v32, v32
	v_max_f32_e32 v31, 0x1e3ce508, v31
	v_add_f32_e32 v27, 1.0, v27
	v_mul_f32_e32 v34, v27, v31
	v_mul_f32_e32 v27, v27, v34
	v_rsq_f32_e32 v27, v27
	v_add_f32_e32 v32, 1.0, v32
	v_rcp_f32_e64 v32, -v32
	v_add_f32_e32 v28, v28, v250
	v_mul_f32_e32 v27, v31, v27
	v_add_f32_e32 v31, v33, v247
	v_mul_f32_e32 v31, 0xbfb8aa3b, v31
	v_mul_f32_e32 v32, v228, v32
	v_exp_f32_e32 v31, v31
	v_add_f32_e32 v34, v32, v32
	v_mul_f32_e32 v34, 0x3fb8aa3b, v34
	v_exp_f32_e32 v34, v34
	v_mul_f32_e32 v28, 0xbfb8aa3b, v28
	v_exp_f32_e32 v28, v28
	v_add_f32_e32 v31, 1.0, v31
	v_and_b32_e32 v35, 0xffff0000, v88
	v_rcp_f32_e64 v31, -v31
	v_mul_f32_e32 v27, v27, v35
	v_cvt_pk_bf16_f32 v27, v30, v27
	v_sub_f32_e32 v30, 1.0, v34
	v_max_f32_e32 v30, 0x1e3ce508, v30
	v_add_f32_e32 v28, 1.0, v28
	v_mul_f32_e32 v33, v28, v30
	v_mul_f32_e32 v31, v229, v31
	v_mul_f32_e32 v28, v28, v33
	v_add_f32_e32 v33, v31, v31
	v_mul_f32_e32 v33, 0x3fb8aa3b, v33
	v_add_f32_e32 v29, v29, v251
	v_exp_f32_e32 v33, v33
	v_mul_f32_e32 v29, 0xbfb8aa3b, v29
	v_exp_f32_e32 v29, v29
	v_rsq_f32_e32 v28, v28
	v_sub_f32_e32 v33, 1.0, v33
	v_max_f32_e32 v33, 0x1e3ce508, v33
	v_add_f32_e32 v29, 1.0, v29
	v_mul_f32_e32 v34, v29, v33
	v_mul_f32_e32 v29, v29, v34
	v_rsq_f32_e32 v29, v29
	v_lshlrev_b32_e32 v36, 16, v89
	v_and_b32_e32 v38, 0xffff0000, v89
	v_mul_f32_e32 v28, v30, v28
	v_mul_f32_e32 v29, v33, v29
	v_mul_f32_e32 v28, v28, v36
	v_mul_f32_e32 v29, v29, v38
	v_cvt_pk_bf16_f32 v28, v32, v28
	v_cvt_pk_bf16_f32 v29, v31, v29
	global_store_dwordx4 v[86:87], v[26:29], off offset:16
	v_add_f32_e32 v94, v94, v162
	v_mul_f32_e32 v94, 0xbfb8aa3b, v94
	v_exp_f32_e32 v94, v94
	v_add_f32_e32 v90, v90, v166
	v_mul_f32_e32 v90, 0xbfb8aa3b, v90
	v_exp_f32_e32 v90, v90
	v_add_f32_e32 v94, 1.0, v94
	v_rcp_f32_e64 v94, -v94
	v_add_f32_e32 v95, v95, v163
	v_mul_f32_e32 v95, 0xbfb8aa3b, v95
	v_add_f32_e32 v90, 1.0, v90
	v_mul_f32_e32 v94, v170, v94
	v_add_f32_e32 v104, v94, v94
	v_mul_f32_e32 v104, 0x3fb8aa3b, v104
	v_exp_f32_e32 v104, v104
	v_exp_f32_e32 v95, v95
	s_waitcnt vmcnt(12)
	v_lshlrev_b32_e32 v102, 16, v70
	v_add_f32_e32 v91, v91, v167
	v_sub_f32_e32 v104, 1.0, v104
	v_max_f32_e32 v104, 0x1e3ce508, v104
	v_mul_f32_e32 v105, v90, v104
	v_mul_f32_e32 v90, v90, v105
	v_rsq_f32_e32 v90, v90
	v_add_f32_e32 v95, 1.0, v95
	v_rcp_f32_e64 v95, -v95
	v_mul_f32_e32 v91, 0xbfb8aa3b, v91
	v_mul_f32_e32 v90, v104, v90
	v_mul_f32_e32 v90, v90, v102
	v_cvt_pk_bf16_f32 v90, v94, v90
	v_mul_f32_e32 v94, v171, v95
	v_add_f32_e32 v95, v94, v94
	v_mul_f32_e32 v95, 0x3fb8aa3b, v95
	v_exp_f32_e32 v95, v95
	v_exp_f32_e32 v91, v91
	v_add_f32_e32 v96, v96, v164
	v_mul_f32_e32 v96, 0xbfb8aa3b, v96
	v_sub_f32_e32 v95, 1.0, v95
	v_max_f32_e32 v95, 0x1e3ce508, v95
	v_add_f32_e32 v91, 1.0, v91
	v_exp_f32_e32 v96, v96
	v_mul_f32_e32 v102, v91, v95
	v_mul_f32_e32 v91, v91, v102
	v_rsq_f32_e32 v91, v91
	v_add_f32_e32 v96, 1.0, v96
	v_rcp_f32_e64 v96, -v96
	v_and_b32_e32 v70, 0xffff0000, v70
	v_mul_f32_e32 v91, v95, v91
	v_mul_f32_e32 v70, v91, v70
	v_cvt_pk_bf16_f32 v91, v94, v70
	v_add_f32_e32 v94, v97, v165
	v_mul_f32_e32 v94, 0xbfb8aa3b, v94
	v_mul_f32_e32 v96, v172, v96
	v_exp_f32_e32 v94, v94
	v_add_f32_e32 v102, v96, v96
	v_mul_f32_e32 v102, 0x3fb8aa3b, v102
	v_add_f32_e32 v92, v92, v168
	v_exp_f32_e32 v102, v102
	v_mul_f32_e32 v92, 0xbfb8aa3b, v92
	v_exp_f32_e32 v92, v92
	v_add_f32_e32 v94, 1.0, v94
	v_rcp_f32_e64 v94, -v94
	v_sub_f32_e32 v70, 1.0, v102
	v_max_f32_e32 v70, 0x1e3ce508, v70
	v_add_f32_e32 v92, 1.0, v92
	v_mul_f32_e32 v95, v92, v70
	v_mul_f32_e32 v94, v173, v94
	v_mul_f32_e32 v92, v92, v95
	v_add_f32_e32 v95, v94, v94
	v_mul_f32_e32 v95, 0x3fb8aa3b, v95
	v_add_f32_e32 v93, v93, v169
	v_exp_f32_e32 v95, v95
	v_mul_f32_e32 v93, 0xbfb8aa3b, v93
	v_exp_f32_e32 v93, v93
	v_rsq_f32_e32 v92, v92
	v_sub_f32_e32 v95, 1.0, v95
	v_max_f32_e32 v95, 0x1e3ce508, v95
	v_add_f32_e32 v93, 1.0, v93
	v_mul_f32_e32 v97, v93, v95
	v_mul_f32_e32 v93, v93, v97
	v_rsq_f32_e32 v93, v93
	v_lshlrev_b32_e32 v103, 16, v71
	v_mul_f32_e32 v70, v70, v92
	v_mul_f32_e32 v70, v70, v103
	v_and_b32_e32 v71, 0xffff0000, v71
	v_cvt_pk_bf16_f32 v92, v96, v70
	v_mul_f32_e32 v70, v95, v93
	v_mul_f32_e32 v70, v70, v71
	v_cvt_pk_bf16_f32 v93, v94, v70
	v_lshlrev_b64 v[70:71], 12, v[202:203]
	v_lshl_add_u64 v[70:71], v[204:205], 0, v[70:71]
	global_store_dwordx4 v[70:71], v[90:93], off
	v_add_f32_e32 v22, v22, v244
	v_mul_f32_e32 v22, 0xbfb8aa3b, v22
	v_exp_f32_e32 v22, v22
	v_add_f32_e32 v18, v18, v248
	v_mul_f32_e32 v18, 0xbfb8aa3b, v18
	v_exp_f32_e32 v18, v18
	v_add_f32_e32 v22, 1.0, v22
	v_rcp_f32_e64 v22, -v22
	v_add_f32_e32 v23, v23, v245
	v_mul_f32_e32 v23, 0xbfb8aa3b, v23
	v_add_f32_e32 v18, 1.0, v18
	v_mul_f32_e32 v22, v226, v22
	v_add_f32_e32 v29, v22, v22
	v_mul_f32_e32 v29, 0x3fb8aa3b, v29
	v_exp_f32_e32 v29, v29
	v_exp_f32_e32 v23, v23
	v_lshlrev_b32_e32 v26, 16, v76
	v_add_f32_e32 v19, v19, v249
	v_sub_f32_e32 v29, 1.0, v29
	v_max_f32_e32 v29, 0x1e3ce508, v29
	v_mul_f32_e32 v30, v18, v29
	v_mul_f32_e32 v18, v18, v30
	v_rsq_f32_e32 v18, v18
	v_add_f32_e32 v23, 1.0, v23
	v_rcp_f32_e64 v23, -v23
	v_mul_f32_e32 v19, 0xbfb8aa3b, v19
	v_mul_f32_e32 v18, v29, v18
	v_mul_f32_e32 v18, v18, v26
	v_cvt_pk_bf16_f32 v18, v22, v18
	v_mul_f32_e32 v22, v227, v23
	v_add_f32_e32 v23, v22, v22
	v_mul_f32_e32 v23, 0x3fb8aa3b, v23
	v_exp_f32_e32 v23, v23
	v_exp_f32_e32 v19, v19
	v_add_f32_e32 v24, v24, v246
	v_mul_f32_e32 v24, 0xbfb8aa3b, v24
	v_sub_f32_e32 v23, 1.0, v23
	v_exp_f32_e32 v24, v24
	v_max_f32_e32 v23, 0x1e3ce508, v23
	v_add_f32_e32 v19, 1.0, v19
	v_mul_f32_e32 v26, v19, v23
	v_mul_f32_e32 v19, v19, v26
	v_rsq_f32_e32 v19, v19
	v_add_f32_e32 v24, 1.0, v24
	v_rcp_f32_e64 v24, -v24
	v_add_f32_e32 v20, v20, v250
	v_mul_f32_e32 v19, v23, v19
	v_add_f32_e32 v23, v25, v247
	v_mul_f32_e32 v23, 0xbfb8aa3b, v23
	v_mul_f32_e32 v24, v228, v24
	v_exp_f32_e32 v23, v23
	v_add_f32_e32 v26, v24, v24
	v_mul_f32_e32 v26, 0x3fb8aa3b, v26
	v_exp_f32_e32 v26, v26
	v_mul_f32_e32 v20, 0xbfb8aa3b, v20
	v_exp_f32_e32 v20, v20
	v_add_f32_e32 v23, 1.0, v23
	v_and_b32_e32 v27, 0xffff0000, v76
	v_rcp_f32_e64 v23, -v23
	v_mul_f32_e32 v19, v19, v27
	v_cvt_pk_bf16_f32 v19, v22, v19
	v_sub_f32_e32 v22, 1.0, v26
	v_max_f32_e32 v22, 0x1e3ce508, v22
	v_add_f32_e32 v20, 1.0, v20
	v_mul_f32_e32 v25, v20, v22
	v_mul_f32_e32 v23, v229, v23
	v_mul_f32_e32 v20, v20, v25
	v_add_f32_e32 v25, v23, v23
	v_mul_f32_e32 v25, 0x3fb8aa3b, v25
	v_add_f32_e32 v21, v21, v251
	v_exp_f32_e32 v25, v25
	v_mul_f32_e32 v21, 0xbfb8aa3b, v21
	v_exp_f32_e32 v21, v21
	v_rsq_f32_e32 v20, v20
	v_sub_f32_e32 v25, 1.0, v25
	v_max_f32_e32 v25, 0x1e3ce508, v25
	v_add_f32_e32 v21, 1.0, v21
	v_mul_f32_e32 v26, v21, v25
	v_mul_f32_e32 v21, v21, v26
	v_rsq_f32_e32 v21, v21
	v_lshlrev_b32_e32 v28, 16, v77
	v_and_b32_e32 v30, 0xffff0000, v77
	v_mul_f32_e32 v20, v22, v20
	v_mul_f32_e32 v21, v25, v21
	v_mul_f32_e32 v20, v20, v28
	v_mul_f32_e32 v21, v21, v30
	v_cvt_pk_bf16_f32 v20, v24, v20
	v_cvt_pk_bf16_f32 v21, v23, v21
	global_store_dwordx4 v[74:75], v[18:21], off offset:16
	v_add_f32_e32 v82, v82, v162
	v_mul_f32_e32 v82, 0xbfb8aa3b, v82
	v_exp_f32_e32 v82, v82
	v_add_f32_e32 v78, v78, v166
	v_mul_f32_e32 v78, 0xbfb8aa3b, v78
	v_exp_f32_e32 v78, v78
	v_add_f32_e32 v82, 1.0, v82
	v_rcp_f32_e64 v82, -v82
	v_add_f32_e32 v83, v83, v163
	v_mul_f32_e32 v83, 0xbfb8aa3b, v83
	v_add_f32_e32 v78, 1.0, v78
	v_mul_f32_e32 v82, v170, v82
	v_add_f32_e32 v92, v82, v82
	v_mul_f32_e32 v92, 0x3fb8aa3b, v92
	v_exp_f32_e32 v92, v92
	v_exp_f32_e32 v83, v83
	v_lshlrev_b32_e32 v90, 16, v66
	v_add_f32_e32 v79, v79, v167
	v_sub_f32_e32 v92, 1.0, v92
	v_max_f32_e32 v92, 0x1e3ce508, v92
	v_mul_f32_e32 v93, v78, v92
	v_mul_f32_e32 v78, v78, v93
	v_rsq_f32_e32 v78, v78
	v_add_f32_e32 v83, 1.0, v83
	v_rcp_f32_e64 v83, -v83
	v_mul_f32_e32 v79, 0xbfb8aa3b, v79
	v_mul_f32_e32 v78, v92, v78
	v_mul_f32_e32 v78, v78, v90
	v_cvt_pk_bf16_f32 v78, v82, v78
	v_mul_f32_e32 v82, v171, v83
	v_add_f32_e32 v83, v82, v82
	v_mul_f32_e32 v83, 0x3fb8aa3b, v83
	v_exp_f32_e32 v83, v83
	v_exp_f32_e32 v79, v79
	v_add_f32_e32 v84, v84, v164
	v_mul_f32_e32 v84, 0xbfb8aa3b, v84
	v_sub_f32_e32 v83, 1.0, v83
	v_max_f32_e32 v83, 0x1e3ce508, v83
	v_add_f32_e32 v79, 1.0, v79
	v_exp_f32_e32 v84, v84
	v_mul_f32_e32 v90, v79, v83
	v_mul_f32_e32 v79, v79, v90
	v_rsq_f32_e32 v79, v79
	v_add_f32_e32 v84, 1.0, v84
	v_rcp_f32_e64 v84, -v84
	v_and_b32_e32 v66, 0xffff0000, v66
	v_mul_f32_e32 v79, v83, v79
	v_mul_f32_e32 v66, v79, v66
	v_cvt_pk_bf16_f32 v79, v82, v66
	v_add_f32_e32 v82, v85, v165
	v_mul_f32_e32 v82, 0xbfb8aa3b, v82
	v_mul_f32_e32 v84, v172, v84
	v_exp_f32_e32 v82, v82
	v_add_f32_e32 v90, v84, v84
	v_mul_f32_e32 v90, 0x3fb8aa3b, v90
	v_add_f32_e32 v80, v80, v168
	v_exp_f32_e32 v90, v90
	v_mul_f32_e32 v80, 0xbfb8aa3b, v80
	v_exp_f32_e32 v80, v80
	v_add_f32_e32 v82, 1.0, v82
	v_rcp_f32_e64 v82, -v82
	v_sub_f32_e32 v66, 1.0, v90
	v_max_f32_e32 v66, 0x1e3ce508, v66
	v_add_f32_e32 v80, 1.0, v80
	v_mul_f32_e32 v83, v80, v66
	v_mul_f32_e32 v82, v173, v82
	v_mul_f32_e32 v80, v80, v83
	v_add_f32_e32 v83, v82, v82
	v_mul_f32_e32 v83, 0x3fb8aa3b, v83
	v_add_f32_e32 v81, v81, v169
	v_exp_f32_e32 v83, v83
	v_mul_f32_e32 v81, 0xbfb8aa3b, v81
	v_exp_f32_e32 v81, v81
	v_rsq_f32_e32 v80, v80
	v_sub_f32_e32 v83, 1.0, v83
	v_max_f32_e32 v83, 0x1e3ce508, v83
	v_add_f32_e32 v81, 1.0, v81
	v_mul_f32_e32 v85, v81, v83
	v_mul_f32_e32 v81, v81, v85
	v_rsq_f32_e32 v81, v81
	v_lshlrev_b32_e32 v91, 16, v67
	v_mul_f32_e32 v66, v66, v80
	v_mul_f32_e32 v66, v66, v91
	v_and_b32_e32 v67, 0xffff0000, v67
	v_cvt_pk_bf16_f32 v80, v84, v66
	v_mul_f32_e32 v66, v83, v81
	v_mul_f32_e32 v66, v66, v67
	v_cvt_pk_bf16_f32 v81, v82, v66
	v_lshlrev_b64 v[66:67], 12, v[200:201]
	v_lshl_add_u64 v[66:67], v[204:205], 0, v[66:67]
	global_store_dwordx4 v[66:67], v[78:81], off
	v_add_f32_e32 v14, v14, v244
	v_mul_f32_e32 v14, 0xbfb8aa3b, v14
	v_exp_f32_e32 v14, v14
	v_add_f32_e32 v10, v10, v248
	v_mul_f32_e32 v10, 0xbfb8aa3b, v10
	v_exp_f32_e32 v10, v10
	v_add_f32_e32 v14, 1.0, v14
	v_rcp_f32_e64 v14, -v14
	v_add_f32_e32 v15, v15, v245
	v_mul_f32_e32 v15, 0xbfb8aa3b, v15
	v_add_f32_e32 v10, 1.0, v10
	v_mul_f32_e32 v14, v226, v14
	v_add_f32_e32 v21, v14, v14
	v_mul_f32_e32 v21, 0x3fb8aa3b, v21
	v_exp_f32_e32 v21, v21
	v_exp_f32_e32 v15, v15
	v_lshlrev_b32_e32 v18, 16, v72
	v_add_f32_e32 v11, v11, v249
	v_sub_f32_e32 v21, 1.0, v21
	v_max_f32_e32 v21, 0x1e3ce508, v21
	v_mul_f32_e32 v22, v10, v21
	v_mul_f32_e32 v10, v10, v22
	v_rsq_f32_e32 v10, v10
	v_add_f32_e32 v15, 1.0, v15
	v_rcp_f32_e64 v15, -v15
	v_mul_f32_e32 v11, 0xbfb8aa3b, v11
	v_mul_f32_e32 v10, v21, v10
	v_mul_f32_e32 v10, v10, v18
	v_cvt_pk_bf16_f32 v10, v14, v10
	v_mul_f32_e32 v14, v227, v15
	v_add_f32_e32 v15, v14, v14
	v_mul_f32_e32 v15, 0x3fb8aa3b, v15
	v_exp_f32_e32 v15, v15
	v_exp_f32_e32 v11, v11
	v_add_f32_e32 v16, v16, v246
	v_mul_f32_e32 v16, 0xbfb8aa3b, v16
	v_sub_f32_e32 v15, 1.0, v15
	v_exp_f32_e32 v16, v16
	v_max_f32_e32 v15, 0x1e3ce508, v15
	v_add_f32_e32 v11, 1.0, v11
	v_mul_f32_e32 v18, v11, v15
	v_mul_f32_e32 v11, v11, v18
	v_rsq_f32_e32 v11, v11
	v_add_f32_e32 v16, 1.0, v16
	v_rcp_f32_e64 v16, -v16
	v_add_f32_e32 v12, v12, v250
	v_mul_f32_e32 v11, v15, v11
	v_add_f32_e32 v15, v17, v247
	v_mul_f32_e32 v15, 0xbfb8aa3b, v15
	v_mul_f32_e32 v16, v228, v16
	v_exp_f32_e32 v15, v15
	v_add_f32_e32 v18, v16, v16
	v_mul_f32_e32 v18, 0x3fb8aa3b, v18
	v_exp_f32_e32 v18, v18
	v_mul_f32_e32 v12, 0xbfb8aa3b, v12
	v_exp_f32_e32 v12, v12
	v_add_f32_e32 v15, 1.0, v15
	v_and_b32_e32 v19, 0xffff0000, v72
	v_rcp_f32_e64 v15, -v15
	v_mul_f32_e32 v11, v11, v19
	v_cvt_pk_bf16_f32 v11, v14, v11
	v_sub_f32_e32 v14, 1.0, v18
	v_max_f32_e32 v14, 0x1e3ce508, v14
	v_add_f32_e32 v12, 1.0, v12
	v_mul_f32_e32 v17, v12, v14
	v_mul_f32_e32 v15, v229, v15
	v_mul_f32_e32 v12, v12, v17
	v_add_f32_e32 v17, v15, v15
	v_mul_f32_e32 v17, 0x3fb8aa3b, v17
	v_add_f32_e32 v13, v13, v251
	v_exp_f32_e32 v17, v17
	v_mul_f32_e32 v13, 0xbfb8aa3b, v13
	v_exp_f32_e32 v13, v13
	v_rsq_f32_e32 v12, v12
	v_sub_f32_e32 v17, 1.0, v17
	v_max_f32_e32 v17, 0x1e3ce508, v17
	v_add_f32_e32 v13, 1.0, v13
	v_mul_f32_e32 v18, v13, v17
	v_mul_f32_e32 v13, v13, v18
	v_rsq_f32_e32 v13, v13
	v_lshlrev_b32_e32 v20, 16, v73
	v_and_b32_e32 v22, 0xffff0000, v73
	v_mul_f32_e32 v12, v14, v12
	v_mul_f32_e32 v13, v17, v13
	v_mul_f32_e32 v12, v12, v20
	v_mul_f32_e32 v13, v13, v22
	v_cvt_pk_bf16_f32 v12, v16, v12
	v_cvt_pk_bf16_f32 v13, v15, v13
	global_store_dwordx4 v[70:71], v[10:13], off offset:16
	v_add_f32_e32 v6, v6, v244
	v_mul_f32_e32 v6, 0xbfb8aa3b, v6
	v_exp_f32_e32 v6, v6
	v_add_f32_e32 v2, v2, v248
	v_mul_f32_e32 v2, 0xbfb8aa3b, v2
	v_exp_f32_e32 v2, v2
	v_add_f32_e32 v6, 1.0, v6
	v_rcp_f32_e64 v6, -v6
	v_add_f32_e32 v7, v7, v245
	v_mul_f32_e32 v7, 0xbfb8aa3b, v7
	v_add_f32_e32 v2, 1.0, v2
	v_mul_f32_e32 v6, v226, v6
	v_add_f32_e32 v13, v6, v6
	v_mul_f32_e32 v13, 0x3fb8aa3b, v13
	v_exp_f32_e32 v13, v13
	v_exp_f32_e32 v7, v7
	v_lshlrev_b32_e32 v10, 16, v68
	v_add_f32_e32 v3, v3, v249
	v_sub_f32_e32 v13, 1.0, v13
	v_max_f32_e32 v13, 0x1e3ce508, v13
	v_mul_f32_e32 v14, v2, v13
	v_mul_f32_e32 v2, v2, v14
	v_rsq_f32_e32 v2, v2
	v_add_f32_e32 v7, 1.0, v7
	v_rcp_f32_e64 v7, -v7
	v_mul_f32_e32 v3, 0xbfb8aa3b, v3
	v_mul_f32_e32 v2, v13, v2
	v_mul_f32_e32 v2, v2, v10
	v_cvt_pk_bf16_f32 v2, v6, v2
	v_mul_f32_e32 v6, v227, v7
	v_add_f32_e32 v7, v6, v6
	v_mul_f32_e32 v7, 0x3fb8aa3b, v7
	v_exp_f32_e32 v7, v7
	v_exp_f32_e32 v3, v3
	v_add_f32_e32 v8, v8, v246
	v_mul_f32_e32 v8, 0xbfb8aa3b, v8
	v_sub_f32_e32 v7, 1.0, v7
	v_exp_f32_e32 v8, v8
	v_max_f32_e32 v7, 0x1e3ce508, v7
	v_add_f32_e32 v3, 1.0, v3
	v_mul_f32_e32 v10, v3, v7
	v_mul_f32_e32 v3, v3, v10
	v_rsq_f32_e32 v3, v3
	v_add_f32_e32 v8, 1.0, v8
	v_rcp_f32_e64 v8, -v8
	v_add_f32_e32 v4, v4, v250
	v_mul_f32_e32 v3, v7, v3
	v_add_f32_e32 v7, v9, v247
	v_mul_f32_e32 v7, 0xbfb8aa3b, v7
	v_mul_f32_e32 v8, v228, v8
	v_exp_f32_e32 v7, v7
	v_add_f32_e32 v10, v8, v8
	v_mul_f32_e32 v10, 0x3fb8aa3b, v10
	v_exp_f32_e32 v10, v10
	v_mul_f32_e32 v4, 0xbfb8aa3b, v4
	v_exp_f32_e32 v4, v4
	v_add_f32_e32 v7, 1.0, v7
	v_and_b32_e32 v11, 0xffff0000, v68
	v_rcp_f32_e64 v7, -v7
	v_mul_f32_e32 v3, v3, v11
	v_cvt_pk_bf16_f32 v3, v6, v3
	v_sub_f32_e32 v6, 1.0, v10
	v_max_f32_e32 v6, 0x1e3ce508, v6
	v_add_f32_e32 v4, 1.0, v4
	v_mul_f32_e32 v9, v4, v6
	v_mul_f32_e32 v7, v229, v7
	v_mul_f32_e32 v4, v4, v9
	v_add_f32_e32 v9, v7, v7
	v_mul_f32_e32 v9, 0x3fb8aa3b, v9
	v_add_f32_e32 v5, v5, v251
	v_exp_f32_e32 v9, v9
	v_mul_f32_e32 v5, 0xbfb8aa3b, v5
	v_exp_f32_e32 v5, v5
	v_rsq_f32_e32 v4, v4
	v_sub_f32_e32 v9, 1.0, v9
	v_max_f32_e32 v9, 0x1e3ce508, v9
	v_add_f32_e32 v5, 1.0, v5
	v_mul_f32_e32 v10, v5, v9
	v_mul_f32_e32 v5, v5, v10
	v_rsq_f32_e32 v5, v5
	v_lshlrev_b32_e32 v12, 16, v69
	v_and_b32_e32 v14, 0xffff0000, v69
	v_mul_f32_e32 v4, v6, v4
	v_mul_f32_e32 v5, v9, v5
	v_mul_f32_e32 v4, v4, v12
	v_mul_f32_e32 v5, v5, v14
	v_cvt_pk_bf16_f32 v4, v8, v4
	v_cvt_pk_bf16_f32 v5, v7, v5
	global_store_dwordx4 v[66:67], v[2:5], off offset:16
	s_andn2_b64 vcc, exec, s[40:41]
	s_mov_b64 s[0:1], -1
	s_cbranch_vccnz .LBB0_993
	s_andn2_b64 vcc, exec, s[44:45]
	s_cbranch_vccnz .LBB0_992
	s_barrier
	s_branch .LBB0_992
